# grid barrier: non-leader workgroups poll the top generation word directly (skip the per-XCD generation hop); on top of state pre-touch
# baseline (speedup 1.0000x reference)
; __device__ __forceinline__ unsigned xb_ld(unsigned* p) { return __hip_atomic_load(p, __ATOMIC_RELAXED, __HIP_MEMORY_SCOPE_AGENT); }
; __device__ __forceinline__ unsigned xb_add(unsigned* p, unsigned v) { return __hip_atomic_fetch_add(p, v, __ATOMIC_RELAXED, __HIP_MEMORY_SCOPE_AGENT); }
; #define XB_SPIN(cond, bar) do { unsigned _sp = 0; while (cond) { __builtin_amdgcn_s_sleep(1); \
;     if ((++_sp & 255u) == 0u) { if (xb_ld(&(bar)[XB_TMO])) break; if (_sp > XB_SPIN_CAP) { atomicAdd(&(bar)[XB_TMO], 1u); break; } } } } while (0)
; __device__ __forceinline__ void xcd_barrier(const XcdBarrier& b, const int wvs) {
;     ...
;     const unsigned old = xb_add(&bar[XB_XSUB(b.x)], 1u);
;     const unsigned gen = old / nloc;
;     if (old + 1u == (gen + 1u) * nloc) {
;       __builtin_amdgcn_fence(__ATOMIC_RELEASE, "agent");
;       asm volatile("s_waitcnt vmcnt(0)" ::: "memory");
;       const unsigned og = xb_add(&bar[XB_TOP], 1u);
;       const unsigned tg = og / nx;
;       if (og + 1u == (tg + 1u) * nx) xb_add(&bar[XB_TOPGEN], 1u);
;       else XB_SPIN(xb_ld(&bar[XB_TOPGEN]) == tg, bar);
;       __builtin_amdgcn_fence(__ATOMIC_ACQUIRE, "agent");
;       xb_add(&bar[XB_XGEN(b.x)], 1u);
;       asm volatile("s_waitcnt vmcnt(0)" ::: "memory");
;     } else {
;       XB_SPIN(xb_ld(&bar[XB_XGEN(b.x)]) == gen, bar);
;       __builtin_amdgcn_fence(__ATOMIC_ACQUIRE, "agent");
;       asm volatile("s_waitcnt vmcnt(0)" ::: "memory");
.LBB0_55:
	s_or_b64 exec, exec, s[6:7]
	v_cvt_f32_u32_e32 v5, v3
	s_waitcnt vmcnt(0)
	v_readfirstlane_b32 s4, v4
	v_sub_u32_e32 v4, 0, v3
	v_rcp_iflag_f32_e32 v5, v5
	v_add_u32_e32 v6, s4, v1
	v_mul_f32_e32 v5, 0x4f7ffffe, v5
	v_cvt_u32_f32_e32 v5, v5
	v_mul_lo_u32 v1, v4, v5
	v_mul_hi_u32 v1, v5, v1
	v_add_u32_e32 v1, v5, v1
	v_mul_hi_u32 v1, v6, v1
	v_mul_lo_u32 v4, v1, v3
	v_sub_u32_e32 v4, v6, v4
	v_add_u32_e32 v5, 1, v1
	v_cmp_ge_u32_e32 vcc, v4, v3
	s_nop 1
	v_cndmask_b32_e32 v1, v1, v5, vcc
	v_sub_u32_e32 v5, v4, v3
	v_cndmask_b32_e32 v4, v4, v5, vcc
	v_add_u32_e32 v5, 1, v1
	v_cmp_ge_u32_e32 vcc, v4, v3
	v_add_u32_e32 v4, 1, v6
	s_nop 0
	v_cndmask_b32_e32 v1, v1, v5, vcc
	v_mul_lo_u32 v5, v3, v1
	v_add_u32_e32 v3, v5, v3
	v_cmp_ne_u32_e32 vcc, v4, v3
	s_and_saveexec_b64 s[4:5], vcc
	s_xor_b64 s[4:5], exec, s[4:5]
	s_cbranch_execz .LBB0_69
	s_waitcnt lgkmcnt(0)
	s_add_u32 s10, s84, 0x27105500
	s_addc_u32 s11, s85, 0
	v_mov_b32_e32 v0, 0
	global_load_dword v0, v0, s[10:11] sc1
	s_waitcnt vmcnt(0)
	v_cmp_eq_u32_e32 vcc, v0, v1
	s_and_saveexec_b64 s[6:7], vcc
	s_cbranch_execz .LBB0_68
	s_add_u32 s8, s84, 0x27102200
	s_addc_u32 s9, s85, 0
	s_mov_b32 s22, 1
	s_mov_b64 s[12:13], 0
	v_mov_b32_e32 v0, 0
	s_branch .LBB0_59

; __device__ __forceinline__ unsigned xb_ld(unsigned* p) { return __hip_atomic_load(p, __ATOMIC_RELAXED, __HIP_MEMORY_SCOPE_AGENT); }
; __device__ __forceinline__ unsigned xb_add(unsigned* p, unsigned v) { return __hip_atomic_fetch_add(p, v, __ATOMIC_RELAXED, __HIP_MEMORY_SCOPE_AGENT); }
; #define XB_SPIN(cond, bar) do { unsigned _sp = 0; while (cond) { __builtin_amdgcn_s_sleep(1); \
;     if ((++_sp & 255u) == 0u) { if (xb_ld(&(bar)[XB_TMO])) break; if (_sp > XB_SPIN_CAP) { atomicAdd(&(bar)[XB_TMO], 1u); break; } } } } while (0)
; __device__ __forceinline__ void xcd_barrier(const XcdBarrier& b, const int wvs) {
;     ...
;     const unsigned old = xb_add(&bar[XB_XSUB(b.x)], 1u);
;     const unsigned gen = old / nloc;
;     if (old + 1u == (gen + 1u) * nloc) {
;       __builtin_amdgcn_fence(__ATOMIC_RELEASE, "agent");
;       asm volatile("s_waitcnt vmcnt(0)" ::: "memory");
;       const unsigned og = xb_add(&bar[XB_TOP], 1u);
;       const unsigned tg = og / nx;
;       if (og + 1u == (tg + 1u) * nx) xb_add(&bar[XB_TOPGEN], 1u);
;       else XB_SPIN(xb_ld(&bar[XB_TOPGEN]) == tg, bar);
;       __builtin_amdgcn_fence(__ATOMIC_ACQUIRE, "agent");
;       xb_add(&bar[XB_XGEN(b.x)], 1u);
;       asm volatile("s_waitcnt vmcnt(0)" ::: "memory");
;     } else {
;       XB_SPIN(xb_ld(&bar[XB_XGEN(b.x)]) == gen, bar);
;       __builtin_amdgcn_fence(__ATOMIC_ACQUIRE, "agent");
;       asm volatile("s_waitcnt vmcnt(0)" ::: "memory");
.LBB0_160:
	s_or_b64 exec, exec, s[6:7]
	v_cvt_f32_u32_e32 v4, v2
	s_waitcnt vmcnt(0)
	v_readfirstlane_b32 s4, v3
	v_sub_u32_e32 v3, 0, v2
	v_rcp_iflag_f32_e32 v4, v4
	v_add_u32_e32 v5, s4, v1
	v_mul_f32_e32 v4, 0x4f7ffffe, v4
	v_cvt_u32_f32_e32 v4, v4
	v_mul_lo_u32 v1, v3, v4
	v_mul_hi_u32 v1, v4, v1
	v_add_u32_e32 v1, v4, v1
	v_mul_hi_u32 v1, v5, v1
	v_mul_lo_u32 v3, v1, v2
	v_sub_u32_e32 v3, v5, v3
	v_add_u32_e32 v4, 1, v1
	v_cmp_ge_u32_e32 vcc, v3, v2
	s_nop 1
	v_cndmask_b32_e32 v1, v1, v4, vcc
	v_sub_u32_e32 v4, v3, v2
	v_cndmask_b32_e32 v3, v3, v4, vcc
	v_add_u32_e32 v4, 1, v1
	v_cmp_ge_u32_e32 vcc, v3, v2
	v_add_u32_e32 v3, 1, v5
	s_nop 0
	v_cndmask_b32_e32 v1, v1, v4, vcc
	v_mul_lo_u32 v4, v2, v1
	v_add_u32_e32 v2, v4, v2
	v_cmp_ne_u32_e32 vcc, v3, v2
	s_and_saveexec_b64 s[4:5], vcc
	s_xor_b64 s[4:5], exec, s[4:5]
	s_cbranch_execz .LBB0_174
	s_waitcnt lgkmcnt(0)
	s_add_u32 s10, s84, 0x27105500
	s_addc_u32 s11, s85, 0
	v_mov_b32_e32 v0, 0
	global_load_dword v0, v0, s[10:11] sc1
	s_waitcnt vmcnt(0)
	v_cmp_eq_u32_e32 vcc, v0, v1
	s_and_saveexec_b64 s[6:7], vcc
	s_cbranch_execz .LBB0_173
	s_add_u32 s8, s84, 0x27102200
	s_addc_u32 s9, s85, 0
	s_mov_b32 s22, 1
	s_mov_b64 s[12:13], 0
	v_mov_b32_e32 v0, 0
	s_branch .LBB0_164
